# dropped the second (redundant) copy of the per-tile accumulator zeroing in the 7 GEMM loops
# baseline (speedup 1.0000x reference)
.LBB0_504:
	s_ashr_i32 s13, s12, 31
	s_lshl_b64 s[14:15], s[12:13], 19
	s_add_u32 s14, s24, s14
	s_addc_u32 s15, s25, s15
	s_ashr_i32 s11, s10, 31
	s_lshl_b64 s[16:17], s[10:11], 19
	s_add_u32 s16, s28, s16
	v_mov_b64_e32 v[0:1], 0
	v_mov_b64_e32 v[2:3], 0
	v_mov_b64_e32 v[4:5], 0
	v_mov_b64_e32 v[6:7], 0
	v_mov_b64_e32 v[8:9], 0
	v_mov_b64_e32 v[10:11], 0
	v_mov_b64_e32 v[12:13], 0
	v_mov_b64_e32 v[14:15], 0
	v_mov_b64_e32 v[16:17], 0
	v_mov_b64_e32 v[18:19], 0
	v_mov_b64_e32 v[20:21], 0
	v_mov_b64_e32 v[22:23], 0
	v_mov_b64_e32 v[24:25], 0
	v_mov_b64_e32 v[26:27], 0
	v_mov_b64_e32 v[28:29], 0
	v_mov_b64_e32 v[30:31], 0
	v_mov_b64_e32 v[32:33], 0
	v_mov_b64_e32 v[34:35], 0
	v_mov_b64_e32 v[36:37], 0
	v_mov_b64_e32 v[38:39], 0
	v_mov_b64_e32 v[40:41], 0
	v_mov_b64_e32 v[42:43], 0
	v_mov_b64_e32 v[44:45], 0
	v_mov_b64_e32 v[46:47], 0
	v_mov_b64_e32 v[48:49], 0
	v_mov_b64_e32 v[50:51], 0
	v_mov_b64_e32 v[52:53], 0
	v_mov_b64_e32 v[54:55], 0
	v_mov_b64_e32 v[56:57], 0
	v_mov_b64_e32 v[58:59], 0
	v_mov_b64_e32 v[60:61], 0
	v_mov_b64_e32 v[62:63], 0
	v_mov_b64_e32 v[64:65], 0
	v_mov_b64_e32 v[66:67], 0
	v_mov_b64_e32 v[68:69], 0
	v_mov_b64_e32 v[70:71], 0
	v_mov_b64_e32 v[72:73], 0
	v_mov_b64_e32 v[74:75], 0
	v_mov_b64_e32 v[76:77], 0
	v_mov_b64_e32 v[78:79], 0
	v_mov_b64_e32 v[80:81], 0
	v_mov_b64_e32 v[82:83], 0
	v_mov_b64_e32 v[84:85], 0
	v_mov_b64_e32 v[86:87], 0
	v_mov_b64_e32 v[88:89], 0
	v_mov_b64_e32 v[90:91], 0
	v_mov_b64_e32 v[92:93], 0
	v_mov_b64_e32 v[94:95], 0
	v_mov_b64_e32 v[96:97], 0
	v_mov_b64_e32 v[98:99], 0
	v_mov_b64_e32 v[100:101], 0
	v_mov_b64_e32 v[102:103], 0
	v_mov_b64_e32 v[104:105], 0
	v_mov_b64_e32 v[106:107], 0
	v_mov_b64_e32 v[108:109], 0
	v_mov_b64_e32 v[110:111], 0
	v_mov_b64_e32 v[112:113], 0
	v_mov_b64_e32 v[114:115], 0
	v_mov_b64_e32 v[116:117], 0
	v_mov_b64_e32 v[118:119], 0
	v_mov_b64_e32 v[120:121], 0
	v_mov_b64_e32 v[122:123], 0
	v_mov_b64_e32 v[124:125], 0
	v_mov_b64_e32 v[126:127], 0
	s_addc_u32 s17, s40, s17
	s_andn2_b64 vcc, exec, s[8:9]
	s_cbranch_vccnz .LBB0_507
	s_and_b64 s[18:19], s[36:37], exec
	s_cselect_b32 s11, s15, s3
	s_cselect_b32 s13, s14, s2
	s_cselect_b32 s26, s17, s1
	s_cselect_b32 s27, s16, s0
	s_add_u32 s34, s0, 0x100
	s_addc_u32 s35, s1, 0
	s_add_u32 s0, s2, 0x40080
	s_addc_u32 s1, s3, 0
	s_mov_b32 s2, 0

.LBB0_633:
	s_ashr_i32 s19, s18, 31
	s_lshl_b64 s[24:25], s[18:19], 17
	s_add_u32 s40, s47, s24
	v_mov_b64_e32 v[0:1], 0
	v_mov_b64_e32 v[2:3], 0
	v_mov_b64_e32 v[4:5], 0
	v_mov_b64_e32 v[6:7], 0
	v_mov_b64_e32 v[8:9], 0
	v_mov_b64_e32 v[10:11], 0
	v_mov_b64_e32 v[12:13], 0
	v_mov_b64_e32 v[14:15], 0
	v_mov_b64_e32 v[16:17], 0
	v_mov_b64_e32 v[18:19], 0
	v_mov_b64_e32 v[20:21], 0
	v_mov_b64_e32 v[22:23], 0
	v_mov_b64_e32 v[24:25], 0
	v_mov_b64_e32 v[26:27], 0
	v_mov_b64_e32 v[28:29], 0
	v_mov_b64_e32 v[30:31], 0
	v_mov_b64_e32 v[32:33], 0
	v_mov_b64_e32 v[34:35], 0
	v_mov_b64_e32 v[36:37], 0
	v_mov_b64_e32 v[38:39], 0
	v_mov_b64_e32 v[40:41], 0
	v_mov_b64_e32 v[42:43], 0
	v_mov_b64_e32 v[44:45], 0
	v_mov_b64_e32 v[46:47], 0
	v_mov_b64_e32 v[48:49], 0
	v_mov_b64_e32 v[50:51], 0
	v_mov_b64_e32 v[52:53], 0
	v_mov_b64_e32 v[54:55], 0
	v_mov_b64_e32 v[56:57], 0
	v_mov_b64_e32 v[58:59], 0
	v_mov_b64_e32 v[60:61], 0
	v_mov_b64_e32 v[62:63], 0
	v_mov_b64_e32 v[68:69], 0
	v_mov_b64_e32 v[70:71], 0
	v_mov_b64_e32 v[72:73], 0
	v_mov_b64_e32 v[74:75], 0
	v_mov_b64_e32 v[76:77], 0
	v_mov_b64_e32 v[78:79], 0
	v_mov_b64_e32 v[80:81], 0
	v_mov_b64_e32 v[82:83], 0
	v_mov_b64_e32 v[84:85], 0
	v_mov_b64_e32 v[86:87], 0
	v_mov_b64_e32 v[88:89], 0
	v_mov_b64_e32 v[90:91], 0
	v_mov_b64_e32 v[92:93], 0
	v_mov_b64_e32 v[94:95], 0
	v_mov_b64_e32 v[96:97], 0
	v_mov_b64_e32 v[98:99], 0
	v_mov_b64_e32 v[100:101], 0
	v_mov_b64_e32 v[102:103], 0
	v_mov_b64_e32 v[104:105], 0
	v_mov_b64_e32 v[106:107], 0
	v_mov_b64_e32 v[108:109], 0
	v_mov_b64_e32 v[110:111], 0
	v_mov_b64_e32 v[112:113], 0
	v_mov_b64_e32 v[114:115], 0
	v_mov_b64_e32 v[116:117], 0
	v_mov_b64_e32 v[118:119], 0
	v_mov_b64_e32 v[120:121], 0
	v_mov_b64_e32 v[122:123], 0
	v_mov_b64_e32 v[124:125], 0
	v_mov_b64_e32 v[126:127], 0
	v_mov_b64_e32 v[128:129], 0
	v_mov_b64_e32 v[130:131], 0
	s_addc_u32 s41, s48, s25
	s_andn2_b64 vcc, exec, s[16:17]
	s_cbranch_vccnz .LBB0_636
	s_and_b64 s[0:1], s[0:1], exec
	s_cselect_b32 s3, s41, s43
	s_cselect_b32 s19, s40, s42
	s_add_u32 s21, s42, 0x100
	s_addc_u32 s24, s43, 0
	s_mov_b32 s25, 0

.LBB0_668:
	s_ashr_i32 s15, s14, 31
	s_lshl_b64 s[18:19], s[14:15], 16
	s_add_u32 s18, s26, s18
	v_mov_b64_e32 v[0:1], 0
	v_mov_b64_e32 v[2:3], 0
	v_mov_b64_e32 v[4:5], 0
	v_mov_b64_e32 v[6:7], 0
	v_mov_b64_e32 v[8:9], 0
	v_mov_b64_e32 v[10:11], 0
	v_mov_b64_e32 v[12:13], 0
	v_mov_b64_e32 v[14:15], 0
	v_mov_b64_e32 v[16:17], 0
	v_mov_b64_e32 v[18:19], 0
	v_mov_b64_e32 v[20:21], 0
	v_mov_b64_e32 v[22:23], 0
	v_mov_b64_e32 v[24:25], 0
	v_mov_b64_e32 v[26:27], 0
	v_mov_b64_e32 v[28:29], 0
	v_mov_b64_e32 v[30:31], 0
	v_mov_b64_e32 v[32:33], 0
	v_mov_b64_e32 v[34:35], 0
	v_mov_b64_e32 v[36:37], 0
	v_mov_b64_e32 v[38:39], 0
	v_mov_b64_e32 v[40:41], 0
	v_mov_b64_e32 v[42:43], 0
	v_mov_b64_e32 v[44:45], 0
	v_mov_b64_e32 v[46:47], 0
	v_mov_b64_e32 v[48:49], 0
	v_mov_b64_e32 v[50:51], 0
	v_mov_b64_e32 v[52:53], 0
	v_mov_b64_e32 v[54:55], 0
	v_mov_b64_e32 v[56:57], 0
	v_mov_b64_e32 v[58:59], 0
	v_mov_b64_e32 v[60:61], 0
	v_mov_b64_e32 v[62:63], 0
	v_mov_b64_e32 v[64:65], 0
	v_mov_b64_e32 v[66:67], 0
	v_mov_b64_e32 v[68:69], 0
	v_mov_b64_e32 v[70:71], 0
	v_mov_b64_e32 v[72:73], 0
	v_mov_b64_e32 v[74:75], 0
	v_mov_b64_e32 v[76:77], 0
	v_mov_b64_e32 v[78:79], 0
	v_mov_b64_e32 v[80:81], 0
	v_mov_b64_e32 v[82:83], 0
	v_mov_b64_e32 v[84:85], 0
	v_mov_b64_e32 v[86:87], 0
	v_mov_b64_e32 v[88:89], 0
	v_mov_b64_e32 v[90:91], 0
	v_mov_b64_e32 v[92:93], 0
	v_mov_b64_e32 v[94:95], 0
	v_mov_b64_e32 v[96:97], 0
	v_mov_b64_e32 v[98:99], 0
	v_mov_b64_e32 v[100:101], 0
	v_mov_b64_e32 v[102:103], 0
	v_mov_b64_e32 v[104:105], 0
	v_mov_b64_e32 v[106:107], 0
	v_mov_b64_e32 v[108:109], 0
	v_mov_b64_e32 v[110:111], 0
	v_mov_b64_e32 v[112:113], 0
	v_mov_b64_e32 v[114:115], 0
	v_mov_b64_e32 v[116:117], 0
	v_mov_b64_e32 v[118:119], 0
	v_mov_b64_e32 v[120:121], 0
	v_mov_b64_e32 v[122:123], 0
	v_mov_b64_e32 v[124:125], 0
	v_mov_b64_e32 v[126:127], 0
	s_addc_u32 s19, s27, s19
	s_andn2_b64 vcc, exec, s[10:11]
	s_cbranch_vccnz .LBB0_671
	s_and_b64 s[2:3], s[2:3], exec
	s_cselect_b32 s15, s19, s39
	s_cselect_b32 s48, s18, s38
	s_add_u32 s49, s38, 0x100
	s_addc_u32 s50, s39, 0
	s_mov_b32 s38, 0

.LBB0_1170:
	s_ashr_i32 s17, s16, 31
	s_lshl_b64 s[18:19], s[16:17], 19
	s_add_u32 s18, s20, s18
	s_addc_u32 s19, s21, s19
	s_ashr_i32 s15, s14, 31
	s_lshl_b64 s[24:25], s[14:15], 19
	s_add_u32 s36, s28, s24
	v_mov_b64_e32 v[0:1], 0
	v_mov_b64_e32 v[2:3], 0
	v_mov_b64_e32 v[4:5], 0
	v_mov_b64_e32 v[6:7], 0
	v_mov_b64_e32 v[8:9], 0
	v_mov_b64_e32 v[10:11], 0
	v_mov_b64_e32 v[12:13], 0
	v_mov_b64_e32 v[14:15], 0
	v_mov_b64_e32 v[16:17], 0
	v_mov_b64_e32 v[18:19], 0
	v_mov_b64_e32 v[20:21], 0
	v_mov_b64_e32 v[22:23], 0
	v_mov_b64_e32 v[24:25], 0
	v_mov_b64_e32 v[26:27], 0
	v_mov_b64_e32 v[28:29], 0
	v_mov_b64_e32 v[30:31], 0
	v_mov_b64_e32 v[32:33], 0
	v_mov_b64_e32 v[34:35], 0
	v_mov_b64_e32 v[36:37], 0
	v_mov_b64_e32 v[38:39], 0
	v_mov_b64_e32 v[40:41], 0
	v_mov_b64_e32 v[42:43], 0
	v_mov_b64_e32 v[44:45], 0
	v_mov_b64_e32 v[46:47], 0
	v_mov_b64_e32 v[48:49], 0
	v_mov_b64_e32 v[50:51], 0
	v_mov_b64_e32 v[52:53], 0
	v_mov_b64_e32 v[54:55], 0
	v_mov_b64_e32 v[56:57], 0
	v_mov_b64_e32 v[58:59], 0
	v_mov_b64_e32 v[60:61], 0
	v_mov_b64_e32 v[62:63], 0
	v_mov_b64_e32 v[64:65], 0
	v_mov_b64_e32 v[66:67], 0
	v_mov_b64_e32 v[68:69], 0
	v_mov_b64_e32 v[70:71], 0
	v_mov_b64_e32 v[72:73], 0
	v_mov_b64_e32 v[74:75], 0
	v_mov_b64_e32 v[76:77], 0
	v_mov_b64_e32 v[78:79], 0
	v_mov_b64_e32 v[80:81], 0
	v_mov_b64_e32 v[82:83], 0
	v_mov_b64_e32 v[84:85], 0
	v_mov_b64_e32 v[86:87], 0
	v_mov_b64_e32 v[88:89], 0
	v_mov_b64_e32 v[90:91], 0
	v_mov_b64_e32 v[92:93], 0
	v_mov_b64_e32 v[94:95], 0
	v_mov_b64_e32 v[96:97], 0
	v_mov_b64_e32 v[98:99], 0
	v_mov_b64_e32 v[100:101], 0
	v_mov_b64_e32 v[102:103], 0
	v_mov_b64_e32 v[104:105], 0
	v_mov_b64_e32 v[106:107], 0
	v_mov_b64_e32 v[108:109], 0
	v_mov_b64_e32 v[110:111], 0
	v_mov_b64_e32 v[112:113], 0
	v_mov_b64_e32 v[114:115], 0
	v_mov_b64_e32 v[116:117], 0
	v_mov_b64_e32 v[118:119], 0
	v_mov_b64_e32 v[120:121], 0
	v_mov_b64_e32 v[122:123], 0
	v_mov_b64_e32 v[124:125], 0
	v_mov_b64_e32 v[126:127], 0
	s_addc_u32 s37, s29, s25
	s_andn2_b64 vcc, exec, s[12:13]
	s_cbranch_vccnz .LBB0_1173
	s_and_b64 s[24:25], s[2:3], exec
	s_cselect_b32 s15, s19, s45
	s_cselect_b32 s17, s18, s44
	s_cselect_b32 s24, s37, s43
	s_cselect_b32 s25, s36, s42
	s_add_u32 s26, s42, 0x100
	s_addc_u32 s27, s43, 0
	s_add_u32 s42, s44, 0x40080
	s_addc_u32 s43, s45, 0
	s_mov_b32 s41, 0

.LBB0_1301:
	s_ashr_i32 s11, s10, 31
	s_lshl_b64 s[12:13], s[10:11], 19
	s_add_u32 s12, s20, s12
	s_addc_u32 s13, s21, s13
	s_ashr_i32 s9, s8, 31
	s_lshl_b64 s[14:15], s[8:9], 19
	s_add_u32 s14, s24, s14
	v_mov_b64_e32 v[0:1], 0
	v_mov_b64_e32 v[2:3], 0
	v_mov_b64_e32 v[4:5], 0
	v_mov_b64_e32 v[6:7], 0
	v_mov_b64_e32 v[8:9], 0
	v_mov_b64_e32 v[10:11], 0
	v_mov_b64_e32 v[12:13], 0
	v_mov_b64_e32 v[14:15], 0
	v_mov_b64_e32 v[16:17], 0
	v_mov_b64_e32 v[18:19], 0
	v_mov_b64_e32 v[20:21], 0
	v_mov_b64_e32 v[22:23], 0
	v_mov_b64_e32 v[24:25], 0
	v_mov_b64_e32 v[26:27], 0
	v_mov_b64_e32 v[28:29], 0
	v_mov_b64_e32 v[30:31], 0
	v_mov_b64_e32 v[32:33], 0
	v_mov_b64_e32 v[34:35], 0
	v_mov_b64_e32 v[36:37], 0
	v_mov_b64_e32 v[38:39], 0
	v_mov_b64_e32 v[40:41], 0
	v_mov_b64_e32 v[42:43], 0
	v_mov_b64_e32 v[44:45], 0
	v_mov_b64_e32 v[46:47], 0
	v_mov_b64_e32 v[48:49], 0
	v_mov_b64_e32 v[50:51], 0
	v_mov_b64_e32 v[52:53], 0
	v_mov_b64_e32 v[54:55], 0
	v_mov_b64_e32 v[56:57], 0
	v_mov_b64_e32 v[58:59], 0
	v_mov_b64_e32 v[60:61], 0
	v_mov_b64_e32 v[62:63], 0
	v_mov_b64_e32 v[64:65], 0
	v_mov_b64_e32 v[66:67], 0
	v_mov_b64_e32 v[68:69], 0
	v_mov_b64_e32 v[70:71], 0
	v_mov_b64_e32 v[72:73], 0
	v_mov_b64_e32 v[74:75], 0
	v_mov_b64_e32 v[76:77], 0
	v_mov_b64_e32 v[78:79], 0
	v_mov_b64_e32 v[80:81], 0
	v_mov_b64_e32 v[82:83], 0
	v_mov_b64_e32 v[84:85], 0
	v_mov_b64_e32 v[86:87], 0
	v_mov_b64_e32 v[88:89], 0
	v_mov_b64_e32 v[90:91], 0
	v_mov_b64_e32 v[92:93], 0
	v_mov_b64_e32 v[94:95], 0
	v_mov_b64_e32 v[96:97], 0
	v_mov_b64_e32 v[98:99], 0
	v_mov_b64_e32 v[100:101], 0
	v_mov_b64_e32 v[102:103], 0
	v_mov_b64_e32 v[104:105], 0
	v_mov_b64_e32 v[106:107], 0
	v_mov_b64_e32 v[108:109], 0
	v_mov_b64_e32 v[110:111], 0
	v_mov_b64_e32 v[112:113], 0
	v_mov_b64_e32 v[114:115], 0
	v_mov_b64_e32 v[116:117], 0
	v_mov_b64_e32 v[118:119], 0
	v_mov_b64_e32 v[120:121], 0
	v_mov_b64_e32 v[122:123], 0
	v_mov_b64_e32 v[124:125], 0
	v_mov_b64_e32 v[126:127], 0
	s_addc_u32 s15, s25, s15
	s_andn2_b64 vcc, exec, s[6:7]
	s_cbranch_vccnz .LBB0_1304
	s_and_b64 s[40:41], s[2:3], exec
	s_cselect_b32 s9, s13, s39
	s_cselect_b32 s11, s12, s38
	s_cselect_b32 s44, s15, s37
	s_cselect_b32 s45, s14, s36
	s_add_u32 s46, s36, 0x100
	s_addc_u32 s47, s37, 0
	s_add_u32 s36, s38, 0x40080
	s_addc_u32 s37, s39, 0
	s_mov_b32 s38, 0

.LBB0_1374:
	s_ashr_i32 s11, s10, 31
	s_lshl_b64 s[12:13], s[10:11], 21
	s_add_u32 s12, s20, s12
	s_addc_u32 s13, s21, s13
	s_ashr_i32 s9, s8, 31
	s_lshl_b64 s[14:15], s[8:9], 21
	s_add_u32 s14, s26, s14
	v_mov_b64_e32 v[0:1], 0
	v_mov_b64_e32 v[2:3], 0
	v_mov_b64_e32 v[4:5], 0
	v_mov_b64_e32 v[6:7], 0
	v_mov_b64_e32 v[8:9], 0
	v_mov_b64_e32 v[10:11], 0
	v_mov_b64_e32 v[12:13], 0
	v_mov_b64_e32 v[14:15], 0
	v_mov_b64_e32 v[16:17], 0
	v_mov_b64_e32 v[18:19], 0
	v_mov_b64_e32 v[20:21], 0
	v_mov_b64_e32 v[22:23], 0
	v_mov_b64_e32 v[24:25], 0
	v_mov_b64_e32 v[26:27], 0
	v_mov_b64_e32 v[28:29], 0
	v_mov_b64_e32 v[30:31], 0
	v_mov_b64_e32 v[32:33], 0
	v_mov_b64_e32 v[34:35], 0
	v_mov_b64_e32 v[36:37], 0
	v_mov_b64_e32 v[38:39], 0
	v_mov_b64_e32 v[40:41], 0
	v_mov_b64_e32 v[42:43], 0
	v_mov_b64_e32 v[44:45], 0
	v_mov_b64_e32 v[46:47], 0
	v_mov_b64_e32 v[48:49], 0
	v_mov_b64_e32 v[50:51], 0
	v_mov_b64_e32 v[52:53], 0
	v_mov_b64_e32 v[54:55], 0
	v_mov_b64_e32 v[56:57], 0
	v_mov_b64_e32 v[58:59], 0
	v_mov_b64_e32 v[60:61], 0
	v_mov_b64_e32 v[62:63], 0
	v_mov_b64_e32 v[64:65], 0
	v_mov_b64_e32 v[66:67], 0
	v_mov_b64_e32 v[68:69], 0
	v_mov_b64_e32 v[70:71], 0
	v_mov_b64_e32 v[72:73], 0
	v_mov_b64_e32 v[74:75], 0
	v_mov_b64_e32 v[76:77], 0
	v_mov_b64_e32 v[78:79], 0
	v_mov_b64_e32 v[80:81], 0
	v_mov_b64_e32 v[82:83], 0
	v_mov_b64_e32 v[84:85], 0
	v_mov_b64_e32 v[86:87], 0
	v_mov_b64_e32 v[88:89], 0
	v_mov_b64_e32 v[90:91], 0
	v_mov_b64_e32 v[92:93], 0
	v_mov_b64_e32 v[94:95], 0
	v_mov_b64_e32 v[96:97], 0
	v_mov_b64_e32 v[98:99], 0
	v_mov_b64_e32 v[100:101], 0
	v_mov_b64_e32 v[102:103], 0
	v_mov_b64_e32 v[104:105], 0
	v_mov_b64_e32 v[106:107], 0
	v_mov_b64_e32 v[108:109], 0
	v_mov_b64_e32 v[110:111], 0
	v_mov_b64_e32 v[112:113], 0
	v_mov_b64_e32 v[114:115], 0
	v_mov_b64_e32 v[116:117], 0
	v_mov_b64_e32 v[118:119], 0
	v_mov_b64_e32 v[120:121], 0
	v_mov_b64_e32 v[122:123], 0
	v_mov_b64_e32 v[124:125], 0
	v_mov_b64_e32 v[126:127], 0
	s_addc_u32 s15, s27, s15
	s_andn2_b64 vcc, exec, s[6:7]
	s_cbranch_vccnz .LBB0_1377
	s_and_b64 s[24:25], s[2:3], exec
	s_cselect_b32 s9, s13, s37
	s_cselect_b32 s11, s12, s36
	s_cselect_b32 s17, s15, s19
	s_cselect_b32 s24, s14, s18
	s_add_u32 s25, s18, 0x100
	s_addc_u32 s48, s19, 0
	s_add_u32 s18, s36, 0x100080
	s_addc_u32 s19, s37, 0
	s_mov_b32 s36, 0

.LBB0_1403:
	v_mov_b64_e32 v[0:1], 0
	v_mov_b64_e32 v[2:3], 0
	v_mov_b64_e32 v[4:5], 0
	v_mov_b64_e32 v[6:7], 0
	v_mov_b64_e32 v[8:9], 0
	v_mov_b64_e32 v[10:11], 0
	v_mov_b64_e32 v[12:13], 0
	v_mov_b64_e32 v[14:15], 0
	v_mov_b64_e32 v[16:17], 0
	v_mov_b64_e32 v[18:19], 0
	v_mov_b64_e32 v[20:21], 0
	v_mov_b64_e32 v[22:23], 0
	v_mov_b64_e32 v[24:25], 0
	v_mov_b64_e32 v[26:27], 0
	v_mov_b64_e32 v[28:29], 0
	v_mov_b64_e32 v[30:31], 0
	v_mov_b64_e32 v[32:33], 0
	v_mov_b64_e32 v[34:35], 0
	v_mov_b64_e32 v[36:37], 0
	v_mov_b64_e32 v[38:39], 0
	v_mov_b64_e32 v[40:41], 0
	v_mov_b64_e32 v[42:43], 0
	v_mov_b64_e32 v[44:45], 0
	v_mov_b64_e32 v[46:47], 0
	v_mov_b64_e32 v[48:49], 0
	v_mov_b64_e32 v[50:51], 0
	v_mov_b64_e32 v[52:53], 0
	v_mov_b64_e32 v[54:55], 0
	v_mov_b64_e32 v[56:57], 0
	v_mov_b64_e32 v[58:59], 0
	v_mov_b64_e32 v[60:61], 0
	v_mov_b64_e32 v[62:63], 0
	v_mov_b64_e32 v[64:65], 0
	v_mov_b64_e32 v[66:67], 0
	v_mov_b64_e32 v[68:69], 0
	v_mov_b64_e32 v[70:71], 0
	v_mov_b64_e32 v[72:73], 0
	v_mov_b64_e32 v[74:75], 0
	v_mov_b64_e32 v[76:77], 0
	v_mov_b64_e32 v[78:79], 0
	v_mov_b64_e32 v[80:81], 0
	v_mov_b64_e32 v[82:83], 0
	v_mov_b64_e32 v[84:85], 0
	v_mov_b64_e32 v[86:87], 0
	v_mov_b64_e32 v[88:89], 0
	v_mov_b64_e32 v[90:91], 0
	v_mov_b64_e32 v[92:93], 0
	v_mov_b64_e32 v[94:95], 0
	v_mov_b64_e32 v[96:97], 0
	v_mov_b64_e32 v[98:99], 0
	v_mov_b64_e32 v[100:101], 0
	v_mov_b64_e32 v[102:103], 0
	v_mov_b64_e32 v[104:105], 0
	v_mov_b64_e32 v[106:107], 0
	v_mov_b64_e32 v[108:109], 0
	v_mov_b64_e32 v[110:111], 0
	v_mov_b64_e32 v[112:113], 0
	v_mov_b64_e32 v[114:115], 0
	v_mov_b64_e32 v[116:117], 0
	v_mov_b64_e32 v[118:119], 0
	v_mov_b64_e32 v[120:121], 0
	v_mov_b64_e32 v[122:123], 0
	v_mov_b64_e32 v[124:125], 0
	v_mov_b64_e32 v[126:127], 0
	s_andn2_b64 vcc, exec, s[10:11]
	s_cbranch_vccnz .LBB0_1407
	s_add_u32 s15, s18, 0x100
	s_addc_u32 s48, s19, 0
	s_add_u32 s18, s36, 0x100080
	s_addc_u32 s19, s37, 0
	s_mov_b32 s36, 0
